# attention A: one static s_setprio 1 for waves 4-7 at phase entry, reset at phase exit
# baseline (speedup 1.0000x reference)
; #define LAS __attribute__((address_space(3)))
; __device__ __forceinline__ void attnA_dma(LAS unsigned char* lds, const unsigned char* ws, int unit, int vbuf, int wid, int lane) {
;     const AUnit a = attnA_decode(unit);
;     const bf16* KA = (const bf16*)(ws + WS_KA); const bf16* VA = (const bf16*)(ws + WS_VA);
;     const unsigned ldsb = (unsigned)(unsigned long)lds;
; #pragma unroll
;     for (int k = 0; k < 6; ++k) { const int idx = wid * 6 + k, lr = 8 * idx + (lane >> 3); int t = a.t0 - 64 + lr; t = t < 0 ? 0 : (t > a.ls - 1 ? a.ls - 1 : t);
;     ...
; #pragma unroll
;     for (int k = 0; k < 6; ++k) { const int idx = wid * 6 + k, dblk = idx / 24, rg = idx % 24; int t = a.t0 - 64 + rg * 16 + (lane >> 2); t = t < 0 ? 0 : (t > a.ls - 1 ? a.ls - 1 : t);
;     ...
; }
; __device__ __forceinline__ void attnA_phase(LAS unsigned char* lds, const unsigned char* ws, int vcu, int G) {
;     const int tid = threadIdx.x, lane = tid & 63, w = __builtin_amdgcn_readfirstlane(tid >> 6), r = lane & 31, h = lane >> 5;
;     constexpr int NU = BATCH * 8 * 3 * 16;
;     const bf16* QA = (const bf16*)(ws + WS_QA);
;     if (vcu < NU) attnA_dma(lds, ws, vcu, AV_OFF, w, lane);
;     int it = 0;
;     bf16x8 qn[4];
;     ...
; #pragma unroll
;         for (int ks = 0; ks < 4; ++ks) qn[ks] = *(const bf16x8*)(QA + qr * 512 + a.head * 64 + 16 * ks + 8 * h); }
.LBB0_216:
	v_readlane_b32 s4, v254, 2
	v_readlane_b32 s5, v254, 3
	s_cmp_lt_i32 s4, 3
	s_cselect_b64 s[4:5], -1, 0
	s_and_b64 s[4:5], s[4:5], s[0:1]
	s_andn2_b64 vcc, exec, s[4:5]
	s_cbranch_vccnz .LBB0_229
	v_writelane_b32 v254, s4, 9
	s_cmpk_gt_i32 s78, 0x17ff
	v_readfirstlane_b32 s11, v160
	v_writelane_b32 v254, s5, 10
	s_cbranch_scc1 .LBB0_228
	s_waitcnt lgkmcnt(0)
	s_cmp_lt_u32 s11, 0x100
	s_cbranch_scc1 .La_noprio
	s_setprio 1
.La_noprio:
	s_add_u32 s66, s76, 0x8000000
	s_addc_u32 s67, s77, 0
	s_ashr_i32 s0, s78, 4
	s_mul_hi_i32 s1, s0, 0x55555556
	s_lshr_b32 s4, s1, 31
	s_add_i32 s1, s1, s4
	s_mul_i32 s1, s1, 3
	s_sub_i32 s4, s0, s1
	s_mul_hi_i32 s0, s78, 0x2aaaaaab
	s_lshr_b32 s1, s0, 3
	s_lshr_b32 s5, s0, 31
	s_ashr_i32 s0, s0, 6
	s_lshl_b32 s7, s4, 1
	s_and_b32 s3, s78, 15
	s_add_i32 s8, s1, s5
	s_add_i32 s0, s0, s5
	s_lshl_b32 s5, -1, s7
	s_ashr_i32 s1, s0, 31
	s_andn2_b32 s5, s3, s5
	s_lshr_b32 s3, s3, s7
	s_lshr_b32 s6, s11, 6
	s_lshl_b64 s[0:1], s[0:1], 12
	s_lshr_b32 s4, 0x1000, s7
	s_lshl_b32 s9, s3, 8
	s_add_u32 s13, s76, 0xc000000
	s_addc_u32 s14, s77, 0
	v_bfe_u32 v20, v160, 3, 3
	s_sub_i32 s10, s9, 64
	s_add_i32 s3, s4, -1
	s_lshl_b32 s4, s8, 7
	s_mul_i32 s8, s6, 48
	v_or_b32_e32 v0, s10, v20
	v_add_u32_e32 v0, s8, v0
	v_min_i32_e32 v1, s3, v0
	v_cmp_lt_i32_e32 vcc, -1, v0
	s_or_b32 s0, s0, s5
	s_and_b32 s68, s4, 0x380
	v_cndmask_b32_e32 v0, 0, v1, vcc
	v_ashrrev_i32_e32 v1, 31, v0
	v_lshlrev_b64 v[0:1], s7, v[0:1]
	s_add_u32 s4, s13, s68
	v_lshl_add_u64 v[0:1], v[0:1], 0, s[0:1]
	s_addc_u32 s5, s14, 0
	v_lshlrev_b64 v[0:1], 10, v[0:1]
	v_lshl_add_u64 v[2:3], s[4:5], 0, v[0:1]
	v_bfe_u32 v0, v160, 4, 2
	v_xor_b32_e32 v0, v0, v160
	s_mul_i32 s12, s6, 6
	v_lshlrev_b32_e32 v0, 3, v0
	v_writelane_b32 v254, s13, 11
	v_and_b32_e32 v0, 56, v0
	s_lshl_b32 s13, s12, 10
	v_writelane_b32 v254, s14, 12
	v_mov_b32_e32 v129, 0
	v_lshlrev_b32_e32 v128, 1, v0
	s_add_i32 s14, s13, 0
	v_lshl_add_u64 v[2:3], v[2:3], 0, v[128:129]
	v_writelane_b32 v254, s14, 13
	s_mov_b32 s13, m0
	s_mov_b32 m0, s14
	s_nop 0
	global_load_lds_dwordx4 v[2:3], off
	s_mov_b32 m0, s13
	s_or_b32 s14, s12, 1
	v_lshl_or_b32 v147, s14, 3, v20
	v_add_u32_e32 v1, s10, v147
	v_min_i32_e32 v2, s3, v1
	v_cmp_lt_i32_e32 vcc, -1, v1
	v_lshrrev_b32_e32 v1, 1, v147
	v_xor_b32_e32 v1, v1, v160
	v_cndmask_b32_e32 v2, 0, v2, vcc
	v_ashrrev_i32_e32 v3, 31, v2
	v_lshlrev_b64 v[2:3], s7, v[2:3]
	v_lshl_add_u64 v[2:3], v[2:3], 0, s[0:1]
	v_lshlrev_b64 v[2:3], 10, v[2:3]
	v_lshlrev_b32_e32 v1, 3, v1
	v_lshl_add_u64 v[4:5], s[4:5], 0, v[2:3]
	v_and_b32_e32 v2, 56, v1
	s_lshl_b32 s13, s14, 10
	v_lshlrev_b32_e32 v128, 1, v2
	s_add_i32 s15, s13, 0
	v_lshl_add_u64 v[4:5], v[4:5], 0, v[128:129]
	v_writelane_b32 v254, s15, 14
	s_mov_b32 s13, m0
	s_mov_b32 m0, s15
	s_nop 0
	global_load_lds_dwordx4 v[4:5], off
	s_mov_b32 m0, s13
	s_add_i32 s15, s12, 2
	v_lshl_or_b32 v148, s15, 3, v20
	v_add_u32_e32 v1, s10, v148
	v_min_i32_e32 v3, s3, v1
	v_cmp_lt_i32_e32 vcc, -1, v1
	v_lshrrev_b32_e32 v1, 1, v148
	v_xor_b32_e32 v1, v1, v160
	v_cndmask_b32_e32 v4, 0, v3, vcc
	v_ashrrev_i32_e32 v5, 31, v4
	v_lshlrev_b64 v[4:5], s7, v[4:5]
	v_lshl_add_u64 v[4:5], v[4:5], 0, s[0:1]
	v_lshlrev_b64 v[4:5], 10, v[4:5]
	v_lshlrev_b32_e32 v1, 3, v1
	v_lshl_add_u64 v[6:7], s[4:5], 0, v[4:5]
	v_and_b32_e32 v4, 56, v1
	s_lshl_b32 s13, s15, 10
	v_lshlrev_b32_e32 v128, 1, v4
	s_add_i32 s16, s13, 0
	v_lshl_add_u64 v[6:7], v[6:7], 0, v[128:129]
	v_writelane_b32 v254, s16, 15
	s_mov_b32 s13, m0
	s_mov_b32 m0, s16
	s_nop 0
	global_load_lds_dwordx4 v[6:7], off
	s_mov_b32 m0, s13
	s_add_i32 s16, s12, 3
	v_lshl_or_b32 v149, s16, 3, v20
	v_add_u32_e32 v1, s10, v149
	v_min_i32_e32 v3, s3, v1
	v_cmp_lt_i32_e32 vcc, -1, v1
	v_lshrrev_b32_e32 v1, 1, v149
	v_xor_b32_e32 v1, v1, v160
	v_cndmask_b32_e32 v6, 0, v3, vcc
	v_ashrrev_i32_e32 v7, 31, v6
	v_lshlrev_b64 v[6:7], s7, v[6:7]
	v_lshl_add_u64 v[6:7], v[6:7], 0, s[0:1]
	v_lshlrev_b64 v[6:7], 10, v[6:7]
	v_lshlrev_b32_e32 v1, 3, v1
	v_lshl_add_u64 v[8:9], s[4:5], 0, v[6:7]
	v_and_b32_e32 v6, 56, v1
	s_lshl_b32 s13, s16, 10
	v_lshlrev_b32_e32 v128, 1, v6
	s_add_i32 s17, s13, 0
	v_lshl_add_u64 v[8:9], v[8:9], 0, v[128:129]
	v_writelane_b32 v254, s17, 16
	s_mov_b32 s13, m0
	s_mov_b32 m0, s17
	s_nop 0
	global_load_lds_dwordx4 v[8:9], off
	s_mov_b32 m0, s13
	s_add_i32 s17, s12, 4
	v_lshl_or_b32 v150, s17, 3, v20
	v_add_u32_e32 v1, s10, v150
	v_min_i32_e32 v3, s3, v1
	v_cmp_lt_i32_e32 vcc, -1, v1
	v_lshrrev_b32_e32 v1, 1, v150
	v_xor_b32_e32 v1, v1, v160
	v_cndmask_b32_e32 v8, 0, v3, vcc
	v_ashrrev_i32_e32 v9, 31, v8
	v_lshlrev_b64 v[8:9], s7, v[8:9]
	v_lshl_add_u64 v[8:9], v[8:9], 0, s[0:1]
	v_lshlrev_b64 v[8:9], 10, v[8:9]
	v_lshlrev_b32_e32 v1, 3, v1
	v_lshl_add_u64 v[10:11], s[4:5], 0, v[8:9]
	v_and_b32_e32 v8, 56, v1
	s_lshl_b32 s13, s17, 10
	v_lshlrev_b32_e32 v128, 1, v8
	s_add_i32 s18, s13, 0
	v_lshl_add_u64 v[10:11], v[10:11], 0, v[128:129]
	v_writelane_b32 v254, s18, 17
	s_mov_b32 s13, m0
	s_mov_b32 m0, s18
	s_nop 0
	global_load_lds_dwordx4 v[10:11], off
	s_mov_b32 m0, s13
	s_add_i32 s18, s12, 5
	v_lshl_or_b32 v151, s18, 3, v20
	v_add_u32_e32 v1, s10, v151
	v_min_i32_e32 v3, s3, v1
	v_cmp_lt_i32_e32 vcc, -1, v1
	v_lshrrev_b32_e32 v1, 1, v151
	v_xor_b32_e32 v1, v1, v160
	v_cndmask_b32_e32 v10, 0, v3, vcc
	v_ashrrev_i32_e32 v11, 31, v10
	v_lshlrev_b64 v[10:11], s7, v[10:11]
	v_lshl_add_u64 v[10:11], v[10:11], 0, s[0:1]
	v_lshlrev_b64 v[10:11], 10, v[10:11]
	v_lshlrev_b32_e32 v1, 3, v1
	v_lshl_add_u64 v[12:13], s[4:5], 0, v[10:11]
	v_and_b32_e32 v10, 56, v1
	v_lshlrev_b32_e32 v128, 1, v10
	s_lshl_b32 s4, s18, 10
	v_lshl_add_u64 v[12:13], v[12:13], 0, v[128:129]
	s_add_i32 s5, s4, 0
; __device__ __forceinline__ void attnA_dma(LAS unsigned char* lds, const unsigned char* ws, int unit, int vbuf, int wid, int lane) {
;     ...
;     for (int k = 0; k < 6; ++k) { const int idx = wid * 6 + k, lr = 8 * idx + (lane >> 3); int t = a.t0 - 64 + lr; t = t < 0 ? 0 : (t > a.ls - 1 ? a.ls - 1 : t);
;     ...
; #pragma unroll
;     for (int k = 0; k < 6; ++k) { const int idx = wid * 6 + k, dblk = idx / 24, rg = idx % 24; int t = a.t0 - 64 + rg * 16 + (lane >> 2); t = t < 0 ? 0 : (t > a.ls - 1 ? a.ls - 1 : t);
	s_mov_b32 s4, m0
	s_mov_b32 m0, s5
	s_nop 0
	global_load_lds_dwordx4 v[12:13], off
	s_mov_b32 m0, s4
	s_add_u32 s4, s76, 0x10000000
	v_writelane_b32 v254, s5, 18
	s_addc_u32 s5, s77, 0
	s_mul_hi_u32 s13, s12, 0xaaaaaab
	v_writelane_b32 v254, s4, 19
	s_add_u32 s4, s4, s68
	s_mul_i32 s13, s13, 24
	v_writelane_b32 v254, s5, 20
	s_addc_u32 s5, s5, 0
	s_sub_i32 s19, s12, s13
	s_lshl_b32 s12, s19, 4
	v_bfe_u32 v152, v160, 2, 4
	v_lshlrev_b32_e32 v1, 3, v160
	s_lshr_b32 s11, s11, 8
	v_writelane_b32 v254, s12, 21
	s_add_i32 s12, s12, s10
	v_and_b32_e32 v12, 24, v1
	v_or_b32_e32 v1, s12, v152
	s_cmp_gt_i32 s12, -1
	v_min_i32_e32 v1, s3, v1
	s_cselect_b64 vcc, -1, 0
	v_cndmask_b32_e32 v14, 0, v1, vcc
	v_ashrrev_i32_e32 v15, 31, v14
	v_lshlrev_b64 v[14:15], s7, v[14:15]
	v_lshl_add_u64 v[14:15], v[14:15], 0, s[0:1]
	s_mov_b32 s69, 0
	v_lshlrev_b64 v[14:15], 10, v[14:15]
	s_lshl_b32 s43, s11, 5
	s_lshl_b32 s12, s11, 6
	s_mulk_i32 s11, 0x6040
	s_add_i32 s20, 0, 0xc080
	v_lshl_add_u64 v[14:15], s[4:5], 0, v[14:15]
	s_mov_b32 s13, s69
	s_add_i32 s21, s11, s20
	s_lshl_b32 s19, s19, 10
	v_lshl_add_u64 v[14:15], v[14:15], 0, s[12:13]
	v_lshlrev_b32_e32 v128, 1, v12
	s_add_i32 s22, s19, s21
	v_lshl_add_u64 v[14:15], v[14:15], 0, v[128:129]
	s_mov_b32 s23, m0
	s_mov_b32 m0, s22
	s_nop 0
	global_load_lds_dwordx4 v[14:15], off
	s_mov_b32 m0, s23
	s_mul_hi_u32 s22, s14, 0xaaaaaab
	s_mul_i32 s22, s22, 24
	s_sub_i32 s14, s14, s22
	s_lshl_b32 s22, s14, 4
	v_writelane_b32 v254, s22, 22
	s_add_i32 s22, s22, s10
	v_or_b32_e32 v1, s22, v152
	s_cmp_gt_i32 s22, -1
	v_min_i32_e32 v1, s3, v1
	s_cselect_b64 vcc, -1, 0
	v_cndmask_b32_e32 v14, 0, v1, vcc
	v_ashrrev_i32_e32 v15, 31, v14
	v_lshlrev_b64 v[14:15], s7, v[14:15]
	v_lshl_add_u64 v[14:15], v[14:15], 0, s[0:1]
	v_lshlrev_b64 v[14:15], 10, v[14:15]
	v_lshl_add_u64 v[14:15], s[4:5], 0, v[14:15]
	s_lshl_b32 s14, s14, 10
	v_lshl_add_u64 v[14:15], v[14:15], 0, s[12:13]
	s_add_i32 s12, s14, s21
	v_lshl_add_u64 v[14:15], v[14:15], 0, v[128:129]
	s_mov_b32 s13, m0
	s_mov_b32 m0, s12
	s_nop 0
	global_load_lds_dwordx4 v[14:15], off
	s_mov_b32 m0, s13
	s_mul_hi_u32 s12, s15, 0xaaaaaaab
	s_lshr_b32 s21, s12, 4
	s_mul_i32 s12, s21, 24
	s_sub_i32 s15, s15, s12
	s_lshl_b32 s12, s15, 4
	v_writelane_b32 v254, s12, 23
	s_add_i32 s12, s12, s10
	v_or_b32_e32 v1, s12, v152
	s_cmp_gt_i32 s12, -1
	v_min_i32_e32 v1, s3, v1
	s_cselect_b64 vcc, -1, 0
	v_cndmask_b32_e32 v14, 0, v1, vcc
	v_ashrrev_i32_e32 v15, 31, v14
	v_lshlrev_b64 v[14:15], s7, v[14:15]
	v_lshl_add_u64 v[14:15], v[14:15], 0, s[0:1]
	v_lshlrev_b64 v[14:15], 10, v[14:15]
	v_lshl_add_u64 v[14:15], s[4:5], 0, v[14:15]
	s_lshl_b32 s12, s21, 6
	s_mov_b32 s13, s69
	s_lshl_b32 s49, s21, 5
	v_lshl_add_u64 v[14:15], v[14:15], 0, s[12:13]
	s_mulk_i32 s21, 0x6040
	s_lshl_b32 s12, s15, 10
	s_add_i32 s12, s12, s21
	v_writelane_b32 v254, s12, 24
	s_add_i32 s12, s12, s20
	v_lshl_add_u64 v[14:15], v[14:15], 0, v[128:129]
	s_mov_b32 s13, m0
	s_mov_b32 m0, s12
	s_nop 0
	global_load_lds_dwordx4 v[14:15], off
	s_mov_b32 m0, s13
	s_mul_hi_u32 s12, s16, 0xaaaaaaab
	s_lshr_b32 s15, s12, 4
	s_mul_i32 s12, s15, 24
	s_sub_i32 s16, s16, s12
	s_lshl_b32 s12, s16, 4
	v_writelane_b32 v254, s12, 25
	s_add_i32 s12, s12, s10
	v_or_b32_e32 v1, s12, v152
	s_cmp_gt_i32 s12, -1
	v_min_i32_e32 v1, s3, v1
	s_cselect_b64 vcc, -1, 0
	v_cndmask_b32_e32 v14, 0, v1, vcc
	v_ashrrev_i32_e32 v15, 31, v14
	v_lshlrev_b64 v[14:15], s7, v[14:15]
	v_lshl_add_u64 v[14:15], v[14:15], 0, s[0:1]
	v_lshlrev_b64 v[14:15], 10, v[14:15]
	v_lshl_add_u64 v[14:15], s[4:5], 0, v[14:15]
	s_lshl_b32 s12, s15, 6
	s_mov_b32 s13, s69
	s_lshl_b32 s51, s15, 5
	v_lshl_add_u64 v[14:15], v[14:15], 0, s[12:13]
	s_mulk_i32 s15, 0x6040
	s_lshl_b32 s12, s16, 10
	s_add_i32 s12, s12, s15
	v_writelane_b32 v254, s12, 26
	s_add_i32 s12, s12, s20
	v_lshl_add_u64 v[14:15], v[14:15], 0, v[128:129]
	s_mov_b32 s13, m0
	s_mov_b32 m0, s12
	s_nop 0
	global_load_lds_dwordx4 v[14:15], off
	s_mov_b32 m0, s13
	s_mul_hi_u32 s12, s17, 0xaaaaaaab
	s_lshr_b32 s15, s12, 4
	s_mul_i32 s12, s15, 24
	s_sub_i32 s16, s17, s12
	s_lshl_b32 s12, s16, 4
	v_writelane_b32 v254, s12, 27
	s_add_i32 s12, s12, s10
	v_or_b32_e32 v1, s12, v152
	s_cmp_gt_i32 s12, -1
	v_min_i32_e32 v1, s3, v1
	s_cselect_b64 vcc, -1, 0
	v_cndmask_b32_e32 v14, 0, v1, vcc
	v_ashrrev_i32_e32 v15, 31, v14
	v_lshlrev_b64 v[14:15], s7, v[14:15]
	v_lshl_add_u64 v[14:15], v[14:15], 0, s[0:1]
	v_lshlrev_b64 v[14:15], 10, v[14:15]
	v_lshl_add_u64 v[14:15], s[4:5], 0, v[14:15]
	s_lshl_b32 s12, s15, 6
	s_mov_b32 s13, s69
	s_lshl_b32 s53, s15, 5
	v_lshl_add_u64 v[14:15], v[14:15], 0, s[12:13]
	s_mulk_i32 s15, 0x6040
	s_lshl_b32 s12, s16, 10
	s_add_i32 s12, s12, s15
	v_writelane_b32 v254, s12, 28
	s_add_i32 s12, s12, s20
	v_lshl_add_u64 v[14:15], v[14:15], 0, v[128:129]
	s_mov_b32 s13, m0
	s_mov_b32 m0, s12
	s_nop 0
	global_load_lds_dwordx4 v[14:15], off
	s_mov_b32 m0, s13
	s_mul_hi_u32 s12, s18, 0xaaaaaaab
	s_lshr_b32 s12, s12, 4
	s_mul_i32 s13, s12, 24
	s_sub_i32 s13, s18, s13
	s_lshl_b32 s15, s13, 4
	s_add_i32 s10, s15, s10
	v_or_b32_e32 v1, s10, v152
	s_cmp_gt_i32 s10, -1
	v_min_i32_e32 v1, s3, v1
	s_cselect_b64 vcc, -1, 0
	v_cndmask_b32_e32 v14, 0, v1, vcc
	v_ashrrev_i32_e32 v15, 31, v14
	v_lshlrev_b64 v[14:15], s7, v[14:15]
	v_lshl_add_u64 v[14:15], v[14:15], 0, s[0:1]
	v_lshlrev_b64 v[14:15], 10, v[14:15]
	v_lshl_add_u64 v[14:15], s[4:5], 0, v[14:15]
	s_lshl_b32 s55, s12, 5
	s_lshl_b32 s4, s12, 6
	s_mulk_i32 s12, 0x6040
	s_lshl_b32 s3, s13, 10
	s_mov_b32 s5, s69
	s_add_i32 s3, s3, s12
	v_lshl_add_u64 v[14:15], v[14:15], 0, s[4:5]
	s_add_i32 s4, s3, s20
	s_lshl_b32 s33, s6, 5
	v_and_b32_e32 v146, 31, v160
; #define LAS __attribute__((address_space(3)))
; __device__ __forceinline__ int crow(int r, int hi) { return (r & 3) + 8 * (r >> 2) + 4 * hi; }
; __device__ __forceinline__ void attnA_dma(LAS unsigned char* lds, const unsigned char* ws, int unit, int vbuf, int wid, int lane) {
;     ...
;     for (int k = 0; k < 6; ++k) { const int idx = wid * 6 + k, dblk = idx / 24, rg = idx % 24; int t = a.t0 - 64 + rg * 16 + (lane >> 2); t = t < 0 ? 0 : (t > a.ls - 1 ? a.ls - 1 : t);
;     ...
; }
; __device__ __forceinline__ void attnA_phase(LAS unsigned char* lds, const unsigned char* ws, int vcu, int G) {
;     const int tid = threadIdx.x, lane = tid & 63, w = __builtin_amdgcn_readfirstlane(tid >> 6), r = lane & 31, h = lane >> 5;
;     constexpr int NU = BATCH * 8 * 3 * 16;
;     const bf16* QA = (const bf16*)(ws + WS_QA);
;     if (vcu < NU) attnA_dma(lds, ws, vcu, AV_OFF, w, lane);
;     int it = 0;
;     bf16x8 qn[4];
;     ...
; #pragma unroll
;         for (int ks = 0; ks < 4; ++ks) qn[ks] = *(const bf16x8*)(QA + qr * 512 + a.head * 64 + 16 * ks + 8 * h); }
;     ...
;             for (int i = 0; i < 16; ++i) { const int cr = crow(i, h);
;                 s[0][i] = (cr >= r) ? s[0][i] : -INFINITY; s[4][i] = (cr <= r) ? s[4][i] : -INFINITY; }
; #pragma unroll
;             for (int j = 0; j < 5; ++j)
; #pragma unroll
;                 for (int i = 0; i < 16; ++i) mx = fmaxf(mx, s[j][i]);
;         } else {
; #pragma unroll
;             for (int j = 0; j < 5; ++j)
; #pragma unroll
;                 for (int i = 0; i < 16; ++i) { const int cr = crow(i, h), rel = 32 * j + cr - 64 - r, tk = a.t0 - 64 + 32 * w + 32 * j + cr;
;                     const bool valid = (rel >= -64) && (rel <= 64) && (tk >= 0) && (tk < a.ls);
;                     const float v = valid ? s[j][i] : -INFINITY; s[j][i] = v; mx = fmaxf(mx, v); }
	v_lshl_add_u64 v[14:15], v[14:15], 0, v[128:129]
	s_mov_b32 s5, m0
	s_mov_b32 m0, s4
	s_nop 0
	global_load_lds_dwordx4 v[14:15], off
	s_mov_b32 m0, s5
	s_add_i32 s4, s33, s9
	v_or_b32_e32 v128, s4, v146
	v_lshlrev_b64 v[14:15], s7, v[128:129]
	v_writelane_b32 v254, s15, 29
	v_lshl_add_u64 v[14:15], v[14:15], 0, s[0:1]
	s_add_u32 s0, s76, 0x3de00000
	v_lshlrev_b64 v[14:15], 10, v[14:15]
	v_writelane_b32 v254, s0, 30
	s_addc_u32 s0, s77, 0
	v_bfe_u32 v19, v160, 5, 1
	v_lshl_add_u64 v[14:15], s[66:67], 0, v[14:15]
	v_writelane_b32 v254, s0, 31
	s_add_i32 s0, s19, s11
	v_lshl_add_u64 v[16:17], v[14:15], 0, s[68:69]
	v_lshlrev_b32_e32 v128, 4, v19
	v_writelane_b32 v254, s0, 32
	s_add_i32 s0, s14, s11
	v_lshlrev_b32_e32 v155, 2, v19
	v_lshl_add_u64 v[16:17], v[16:17], 0, v[128:129]
	v_writelane_b32 v254, s0, 33
	v_cmp_gt_u32_e64 s[0:1], v155, v146
	global_load_dwordx4 v[112:115], v[16:17], off
	global_load_dwordx4 v[116:119], v[16:17], off offset:32
	global_load_dwordx4 v[120:123], v[16:17], off offset:64
	global_load_dwordx4 v[124:127], v[16:17], off offset:96
	v_writelane_b32 v254, s0, 34
	v_or_b32_e32 v157, 1, v155
	v_or_b32_e32 v158, 2, v155
	v_writelane_b32 v254, s1, 35
	v_sub_co_u32_e64 v13, s[0:1], v157, v146
	v_or_b32_e32 v159, 3, v155
	s_nop 0
	v_writelane_b32 v254, s0, 36
	v_or_b32_e32 v161, 8, v155
	v_and_b32_e32 v18, 63, v160
	v_writelane_b32 v254, s1, 37
	v_sub_co_u32_e64 v15, s[0:1], v158, v146
	v_or_b32_e32 v162, 9, v155
	s_nop 0
	v_writelane_b32 v254, s0, 38
	v_cmp_gt_u32_e64 s[40:41], 32, v18
	v_bfe_u32 v7, v160, 2, 2
	v_writelane_b32 v254, s1, 39
	v_cmp_gt_u32_e64 s[0:1], v158, v146
	v_or3_b32 v7, v7, v155, s33
	v_lshlrev_b32_e32 v9, 1, v160
	v_writelane_b32 v254, s0, 40
	v_lshrrev_b32_e32 v3, 1, v160
	v_bfe_u32 v5, v160, 1, 3
	v_writelane_b32 v254, s1, 41
	v_sub_co_u32_e64 v16, s[0:1], v159, v146
	v_lshl_add_u32 v7, v7, 6, 0
	s_nop 0
	v_writelane_b32 v254, s0, 42
	v_and_b32_e32 v9, 32, v9
	v_or_b32_e32 v163, 10, v155
	v_writelane_b32 v254, s1, 43
	v_cmp_gt_u32_e64 s[0:1], v159, v146
	v_lshlrev_b32_e32 v14, 3, v19
	v_add3_u32 v156, v7, v9, v12
	v_writelane_b32 v254, s0, 44
	v_bitop3_b32 v3, v19, v3, 7 bitop3:0x78
	v_bitop3_b32 v7, v19, v5, 2 bitop3:0x36
	v_writelane_b32 v254, s1, 45
	v_sub_co_u32_e64 v17, s[0:1], v161, v146
	v_bitop3_b32 v9, v19, v5, 4 bitop3:0x36
	s_nop 0
	v_writelane_b32 v254, s0, 46
	v_bitop3_b32 v5, v19, v5, 6 bitop3:0x36
	v_or_b32_e32 v164, 11, v155
	v_writelane_b32 v254, s1, 47
	v_cmp_gt_u32_e64 s[0:1], v161, v146
	v_or_b32_e32 v154, s8, v20
	v_or_b32_e32 v165, 16, v155
	v_writelane_b32 v254, s0, 48
	v_or_b32_e32 v166, 17, v155
	v_or_b32_e32 v167, 18, v155
	v_writelane_b32 v254, s1, 49
	v_sub_co_u32_e64 v18, s[0:1], v162, v146
	v_or_b32_e32 v168, 19, v155
	s_nop 0
	v_writelane_b32 v254, s0, 50
	v_or_b32_e32 v169, 24, v155
	v_or_b32_e32 v170, 25, v155
	v_writelane_b32 v254, s1, 51
	v_cmp_gt_u32_e64 s[0:1], v162, v146
	v_or_b32_e32 v171, 26, v155
	v_or_b32_e32 v172, 27, v155
	v_writelane_b32 v254, s0, 52
	v_sub_co_u32_e64 v11, s[4:5], v155, v146
	s_nop 0
	v_writelane_b32 v254, s1, 53
	v_sub_co_u32_e64 v19, s[0:1], v163, v146
	s_movk_i32 s38, 0x81
	s_nop 0
	v_writelane_b32 v254, s0, 54
	v_or_b32_e32 v153, s33, v146
	v_lshl_add_u32 v1, v153, 7, 0
	v_writelane_b32 v254, s1, 55
	v_cmp_gt_u32_e64 s[0:1], v163, v146
	v_lshlrev_b32_e32 v3, 4, v3
	v_lshlrev_b32_e32 v7, 4, v7
	v_writelane_b32 v254, s0, 56
	v_lshlrev_b32_e32 v9, 4, v9
	v_lshlrev_b32_e32 v5, 4, v5
	v_writelane_b32 v254, s1, 57
	v_sub_co_u32_e64 v20, s[0:1], v164, v146
	v_lshlrev_b32_e32 v130, 1, v0
	s_nop 0
	v_writelane_b32 v254, s0, 58
	v_mbcnt_lo_u32_b32 v0, -1, 0
	v_add_u32_e32 v173, v1, v3
	v_writelane_b32 v254, s1, 59
	v_cmp_gt_u32_e64 s[0:1], v164, v146
	v_add_u32_e32 v174, v1, v7
	v_add_u32_e32 v175, v1, v9
	v_writelane_b32 v254, s0, 60
	v_add_u32_e32 v176, v1, v5
	v_lshlrev_b32_e32 v132, 1, v2
	v_writelane_b32 v254, s1, 61
	v_sub_co_u32_e64 v21, s[0:1], v165, v146
	v_lshlrev_b32_e32 v134, 1, v4
	s_nop 0
	v_writelane_b32 v254, s0, 62
	v_lshlrev_b32_e32 v136, 1, v6
	v_lshlrev_b32_e32 v138, 1, v8
	v_writelane_b32 v254, s1, 63
	v_cmp_gt_u32_e64 s[0:1], v165, v146
	v_lshlrev_b32_e32 v140, 1, v10
	s_lshl_b32 s48, s43, 1
	v_writelane_b32 v255, s0, 0
	v_lshlrev_b32_e32 v142, 1, v12
	s_lshl_b32 s50, s49, 1
; __device__ __forceinline__ int crow(int r, int hi) { return (r & 3) + 8 * (r >> 2) + 4 * hi; }
; __device__ __forceinline__ void attnA_phase(LAS unsigned char* lds, const unsigned char* ws, int vcu, int G) {
;     ...
;         if ((a.t0 - 64 + 32 * w >= 0) && (a.t0 + 32 * w + 96 <= a.ls)) {
; #pragma unroll
;             for (int i = 0; i < 16; ++i) { const int cr = crow(i, h);
;                 s[0][i] = (cr >= r) ? s[0][i] : -INFINITY; s[4][i] = (cr <= r) ? s[4][i] : -INFINITY; }
; #pragma unroll
;             for (int j = 0; j < 5; ++j)
; #pragma unroll
;                 for (int i = 0; i < 16; ++i) mx = fmaxf(mx, s[j][i]);
;         } else {
; #pragma unroll
;             for (int j = 0; j < 5; ++j)
; #pragma unroll
;                 for (int i = 0; i < 16; ++i) { const int cr = crow(i, h), rel = 32 * j + cr - 64 - r, tk = a.t0 - 64 + 32 * w + 32 * j + cr;
;                     const bool valid = (rel >= -64) && (rel <= 64) && (tk >= 0) && (tk < a.ls);
;                     const float v = valid ? s[j][i] : -INFINITY; s[j][i] = v; mx = fmaxf(mx, v); }
	v_writelane_b32 v255, s1, 1
	v_sub_co_u32_e64 v22, s[0:1], v166, v146
	s_lshl_b32 s52, s51, 1
	s_nop 0
	v_writelane_b32 v255, s0, 2
	s_lshl_b32 s54, s53, 1
	s_lshl_b32 s62, s55, 1
	v_writelane_b32 v255, s1, 3
	v_cmp_gt_u32_e64 s[0:1], v166, v146
	s_mov_b32 s43, 0xff800000
	v_mbcnt_hi_u32_b32 v177, -1, v0
	v_writelane_b32 v255, s0, 4
	v_lshlrev_b32_e32 v144, 1, v14
	v_mov_b32_e32 v178, 0xff800000
	v_writelane_b32 v255, s1, 5
	v_sub_co_u32_e64 v23, s[0:1], v167, v146
	s_mov_b32 s79, 0
	s_nop 0
	v_writelane_b32 v255, s0, 6
	s_mov_b32 s84, s78
	s_nop 0
	v_writelane_b32 v255, s1, 7
	v_cmp_gt_u32_e64 s[0:1], v167, v146
	s_nop 1
	v_writelane_b32 v255, s0, 8
	s_nop 1
	v_writelane_b32 v255, s1, 9
	v_sub_co_u32_e64 v24, s[0:1], v168, v146
	v_cmp_gt_u32_e64 s[90:91], s38, v24
	s_nop 0
	v_writelane_b32 v255, s0, 10
	s_nop 1
	v_writelane_b32 v255, s1, 11
	v_cmp_gt_u32_e64 s[0:1], v168, v146
	s_nop 1
	v_writelane_b32 v255, s0, 12
	s_nop 1
	v_writelane_b32 v255, s1, 13
	v_sub_co_u32_e64 v25, s[0:1], v169, v146
	v_cmp_gt_u32_e64 s[92:93], s38, v25
	s_nop 0
	v_writelane_b32 v255, s0, 14
	s_nop 1
	v_writelane_b32 v255, s1, 15
	v_cmp_gt_u32_e64 s[0:1], v169, v146
	s_nop 1
	v_writelane_b32 v255, s0, 16
	s_nop 1
	v_writelane_b32 v255, s1, 17
	v_sub_co_u32_e64 v26, s[0:1], v170, v146
	v_cmp_gt_u32_e64 s[94:95], s38, v26
	s_nop 0
	v_writelane_b32 v255, s0, 18
	s_nop 1
	v_writelane_b32 v255, s1, 19
	v_cmp_gt_u32_e64 s[0:1], v170, v146
	s_nop 1
	v_writelane_b32 v255, s0, 20
	s_nop 1
	v_writelane_b32 v255, s1, 21
	v_sub_co_u32_e64 v27, s[0:1], v171, v146
	v_cmp_gt_u32_e64 s[96:97], s38, v27
	s_nop 0
	v_writelane_b32 v255, s0, 22
	s_nop 1
	v_writelane_b32 v255, s1, 23
	v_cmp_gt_u32_e64 s[0:1], v171, v146
	s_nop 1
	v_writelane_b32 v255, s0, 24
	s_nop 1
	v_writelane_b32 v255, s1, 25
	v_sub_co_u32_e64 v28, s[0:1], v172, v146
	s_nop 1
	v_writelane_b32 v255, s0, 26
	s_nop 1
	v_writelane_b32 v255, s1, 27
	v_cmp_gt_u32_e64 s[0:1], v172, v146
	s_nop 1
	v_writelane_b32 v255, s0, 28
	s_nop 1
	v_writelane_b32 v255, s1, 29
	v_cmp_gt_u32_e64 s[0:1], s38, v11
	v_sub_u32_e32 v11, 0x80, v146
	s_nop 0
	v_writelane_b32 v255, s0, 30
	s_nop 1
	v_writelane_b32 v255, s1, 31
	v_cmp_gt_u32_e64 s[0:1], s38, v13
	v_add_u32_e32 v13, v155, v11
	v_cmp_gt_u32_e64 s[6:7], s38, v13
	v_writelane_b32 v255, s0, 32
	v_add_u32_e32 v13, v157, v11
	v_cmp_gt_u32_e64 s[8:9], s38, v13
	v_writelane_b32 v255, s1, 33
	v_cmp_gt_u32_e64 s[0:1], s38, v15
	v_add_u32_e32 v13, v158, v11
	v_cmp_gt_u32_e64 s[10:11], s38, v13
	v_writelane_b32 v255, s0, 34
	v_add_u32_e32 v13, v159, v11
	v_cmp_gt_u32_e64 s[12:13], s38, v13
	v_writelane_b32 v255, s1, 35
	v_cmp_gt_u32_e64 s[0:1], s38, v16
	v_add_u32_e32 v13, v161, v11
	v_cmp_gt_u32_e64 s[14:15], s38, v13
	v_writelane_b32 v255, s0, 36
	v_add_u32_e32 v13, v162, v11
	v_cmp_gt_u32_e64 s[16:17], s38, v13
	v_writelane_b32 v255, s1, 37
	v_cmp_gt_u32_e64 s[0:1], s38, v17
	v_add_u32_e32 v13, v163, v11
	v_cmp_gt_u32_e64 s[18:19], s38, v13
	v_writelane_b32 v255, s0, 38
	v_add_u32_e32 v13, v164, v11
	v_cmp_gt_u32_e64 s[20:21], s38, v13
	v_writelane_b32 v255, s1, 39
	v_cmp_gt_u32_e64 s[0:1], s38, v18
	v_add_u32_e32 v13, v165, v11
	v_cmp_gt_u32_e64 s[22:23], s38, v13
	v_writelane_b32 v255, s0, 40
	v_add_u32_e32 v13, v166, v11
	v_cmp_gt_u32_e64 s[24:25], s38, v13
	v_writelane_b32 v255, s1, 41
	v_cmp_gt_u32_e64 s[0:1], s38, v19
	v_add_u32_e32 v13, v167, v11
	v_cmp_gt_u32_e64 s[26:27], s38, v13
	v_writelane_b32 v255, s0, 42
	v_add_u32_e32 v13, v168, v11
	v_cmp_gt_u32_e64 s[28:29], s38, v13
	v_writelane_b32 v255, s1, 43
	v_cmp_gt_u32_e64 s[0:1], s38, v20
	v_add_u32_e32 v13, v169, v11
	v_cmp_gt_u32_e64 s[30:31], s38, v13
	v_writelane_b32 v255, s0, 44
	v_add_u32_e32 v13, v170, v11
	v_cmp_gt_u32_e64 s[34:35], s38, v13
	v_writelane_b32 v255, s1, 45
	v_cmp_gt_u32_e64 s[0:1], s38, v21
	v_add_u32_e32 v13, v171, v11
	v_add_u32_e32 v11, v172, v11
	v_writelane_b32 v255, s0, 46
	v_cmp_gt_u32_e64 s[36:37], s38, v13
	s_nop 0
	v_writelane_b32 v255, s1, 47
	v_cmp_gt_u32_e64 s[0:1], s38, v22
	s_nop 1
	v_writelane_b32 v255, s0, 48
	s_nop 1
	v_writelane_b32 v255, s1, 49
	v_cmp_gt_u32_e64 s[0:1], s38, v23
	s_nop 1
	v_writelane_b32 v255, s0, 50
	s_nop 1
	v_writelane_b32 v255, s1, 51
	v_cmp_gt_u32_e64 s[0:1], s38, v28
	v_cmp_gt_u32_e64 s[38:39], s38, v11
	s_branch .LBB0_220

; __device__ __forceinline__ void attnA_phase(LAS unsigned char* lds, const unsigned char* ws, int vcu, int G) {
;     ...
;         if (h == 0) LSE[qrow * 8 + a.head] = mx + __builtin_amdgcn_logf(l);
;     }
;     __syncthreads();
; }
.LBB0_228:
	s_setprio 0
	v_readlane_b32 s4, v254, 9
	v_readlane_b32 s5, v254, 10
	s_waitcnt vmcnt(0) lgkmcnt(0)
	s_barrier
